# P6a head loop: the eight first-half r/k/v loads issued together at the top of the head iteration (staging registers), second-half loads started as staging frees up
# speedup vs baseline: 1.0162x; 1.0066x over previous
; #define LAS __attribute__((address_space(3)))
; __device__ __forceinline__ void prep_rwkv_phase(const Params& p, LAS unsigned char* lds, int gw, int ngw, int wave, int lane) {
;     ...
;     for (int h = 0; h < 8; ++h) {
;         if (h < 7) prep_w_load(p, h + 1, tid, wreg);
;         if (active) {
;         {
;             f32x4 accG[4];
; #pragma unroll
;             for (int i = 0; i < 4; ++i) { accG[i] = (f32x4){0.f, 0.f, 0.f, 0.f};
; #pragma unroll
;                 for (int ks = 0; ks < 4; ++ks) {
;                     const bf16x8 wg = *(const LAS bf16x8*)(WG + (i * 16 + fr) * 136 + ks * 32 + fq * 8), ag = *(const LAS bf16x8*)(act + fr * 264 + 128 + ks * 32 + fq * 8);
;                     accG[i] = __builtin_amdgcn_mfma_f32_16x16x32_bf16(wg, ag, accG[i], 0, 0, 0); } }
; #pragma unroll
;             for (int hf = 0; hf < 2; ++hf)
;                 *(u32x4*)(G + (size_t)m * 512 + h * 64 + fq * 16 + hf * 8) = (u32x4){pk2(accG[2 * hf][0], accG[2 * hf][1]), pk2(accG[2 * hf][2], accG[2 * hf][3]), pk2(accG[2 * hf + 1][0], accG[2 * hf + 1][1]), pk2(accG[2 * hf + 1][2], accG[2 * hf + 1][3])};
;         }
;         f32x4 accD[4], accA[4];
; #pragma unroll
;         for (int i = 0; i < 4; ++i) {
;             accD[i] = (f32x4){0.f, 0.f, 0.f, 0.f}; accA[i] = accD[i];
; #pragma unroll
;             for (int ks = 0; ks < 2; ++ks) {
;                 const bf16x8 wd = *(const LAS bf16x8*)(WD + (i * 16 + fr) * 72 + ks * 32 + fq * 8), ad = *(const LAS bf16x8*)(act + fr * 264 + ks * 32 + fq * 8);
;                 accD[i] = __builtin_amdgcn_mfma_f32_16x16x32_bf16(wd, ad, accD[i], 0, 0, 0);
;                 const bf16x8 wa = *(const LAS bf16x8*)(WA + (i * 16 + fr) * 72 + ks * 32 + fq * 8), aa = *(const LAS bf16x8*)(act + fr * 264 + 64 + ks * 32 + fq * 8);
;                 accA[i] = __builtin_amdgcn_mfma_f32_16x16x32_bf16(wa, aa, accA[i], 0, 0, 0);
;             }
;         }
;         float nk = 0.f, sbr = 0.f, skr = 0.f, sbo = 0.f;
;         u32x4 kcs[2], kps[2];
; #pragma unroll
;         for (int hf = 0; hf < 2; ++hf) {
;             const int o_ = h * 64 + fq * 16 + hf * 8;
;             kcs[hf] = *(const u32x4*)(prow + 512 + o_); kps[hf] = *(const u32x4*)(pprev + 512 + o_); if (first) kps[hf] = (u32x4){0u, 0u, 0u, 0u};
;             const u32x4 kc = kcs[hf], kp = kps[hf];
; #pragma unroll
.LBB0_857:
	s_andn2_b64 vcc, exec, s[20:21]
	s_cbranch_vccnz .LBB0_861
	v_lshlrev_b32_e32 v96, 1, v144
	v_add_co_u32_e32 v94, vcc, v136, v96
	s_nop 1
	v_addc_co_u32_e32 v95, vcc, 0, v137, vcc
	global_load_dwordx4 v[98:101], v[94:95], off offset:1024
	global_load_dwordx4 v[102:105], v[94:95], off offset:1040
	global_load_dwordx4 v[106:109], v[94:95], off offset:2048
	global_load_dwordx4 v[110:113], v[94:95], off
	v_add_co_u32_e32 v94, vcc, v134, v96
	s_nop 1
	v_addc_co_u32_e32 v95, vcc, 0, v135, vcc
	global_load_dwordx4 v[114:117], v[94:95], off offset:1040
	global_load_dwordx4 v[122:125], v[94:95], off offset:2048
	global_load_dwordx4 v[126:129], v[94:95], off offset:1024
	global_load_dwordx4 v[240:243], v[94:95], off
	s_waitcnt lgkmcnt(1)
	ds_read_b128 v[20:23], v222
	ds_read_b128 v[24:27], v213 offset:256
	ds_read_b128 v[28:31], v222 offset:64
	ds_read_b128 v[32:35], v213 offset:320
	ds_read_b128 v[36:39], v222 offset:4352
	ds_read_b128 v[40:43], v222 offset:4416
	ds_read_b128 v[44:47], v222 offset:128
	ds_read_b128 v[48:51], v222 offset:192
	s_waitcnt lgkmcnt(6)
	v_mfma_f32_16x16x32_bf16 v[20:23], v[20:23], v[24:27], 0
	v_lshl_add_u64 v[0:1], s[92:93], 0, v[142:143]
	v_add_co_u32_e32 v0, vcc, s28, v0
	s_waitcnt lgkmcnt(4)
	v_mfma_f32_16x16x32_bf16 v[20:23], v[28:31], v[32:35], v[20:23]
	ds_read_b128 v[28:31], v213 offset:384
	ds_read_b128 v[52:55], v213 offset:448
	v_addc_co_u32_e32 v1, vcc, 0, v1, vcc
	s_waitcnt lgkmcnt(5)
	v_mfma_f32_16x16x32_bf16 v[36:39], v[36:39], v[24:27], 0
	v_ashrrev_i32_e32 v145, 31, v144
	v_add_u32_e32 v187, s31, v97
	v_add_u32_e32 v2, 0x11040, v187
	s_waitcnt lgkmcnt(1)
	v_mfma_f32_16x16x32_bf16 v[20:23], v[44:47], v[28:31], v[20:23]
	ds_read_b128 v[44:47], v222 offset:4480
	v_mfma_f32_16x16x32_bf16 v[36:39], v[40:43], v[32:35], v[36:39]
	ds_read_b128 v[40:43], v222 offset:4544
	s_waitcnt lgkmcnt(1)
	v_mfma_f32_16x16x32_bf16 v[36:39], v[44:47], v[28:31], v[36:39]
	ds_read_b128 v[44:47], v222 offset:8704
	s_waitcnt lgkmcnt(1)
	v_mfma_f32_16x16x32_bf16 v[36:39], v[40:43], v[52:55], v[36:39]
	ds_read_b128 v[40:43], v222 offset:8768
	v_mfma_f32_16x16x32_bf16 v[20:23], v[48:51], v[52:55], v[20:23]
	ds_read_b128 v[48:51], v222 offset:8832
	s_waitcnt lgkmcnt(2)
	v_mfma_f32_16x16x32_bf16 v[44:47], v[44:47], v[24:27], 0
	s_waitcnt lgkmcnt(1)
	v_mfma_f32_16x16x32_bf16 v[40:43], v[40:43], v[32:35], v[44:47]
	s_nop 2
	v_cvt_pk_bf16_f32 v20, v20, v21
	v_cvt_pk_bf16_f32 v21, v22, v23
	v_cvt_pk_bf16_f32 v22, v36, v37
	ds_read_b128 v[44:47], v222 offset:8896
	s_waitcnt lgkmcnt(1)
	v_mfma_f32_16x16x32_bf16 v[40:43], v[48:51], v[28:31], v[40:43]
	ds_read_b128 v[48:51], v222 offset:13056
	ds_read_b128 v[56:59], v222 offset:13120
	v_cvt_pk_bf16_f32 v23, v38, v39
	s_waitcnt lgkmcnt(1)
	v_mfma_f32_16x16x32_bf16 v[24:27], v[48:51], v[24:27], 0
	v_mfma_f32_16x16x32_bf16 v[40:43], v[44:47], v[52:55], v[40:43]
	ds_read_b128 v[44:47], v222 offset:13184
	ds_read_b128 v[60:63], v222 offset:13248
	global_store_dwordx4 v[0:1], v[20:23], off
	s_waitcnt lgkmcnt(2)
	v_mfma_f32_16x16x32_bf16 v[24:27], v[56:59], v[32:35], v[24:27]
	s_nop 2
	v_cvt_pk_bf16_f32 v20, v40, v41
	v_cvt_pk_bf16_f32 v21, v42, v43
	s_waitcnt lgkmcnt(1)
	v_mfma_f32_16x16x32_bf16 v[24:27], v[44:47], v[28:31], v[24:27]
	s_waitcnt lgkmcnt(0)
	v_mfma_f32_16x16x32_bf16 v[22:25], v[60:63], v[52:55], v[24:27]
	s_nop 7
	v_cvt_pk_bf16_f32 v22, v22, v23
	v_cvt_pk_bf16_f32 v23, v24, v25
	global_store_dwordx4 v[0:1], v[20:23], off offset:16
	v_lshlrev_b64 v[0:1], 1, v[144:145]
	v_lshl_add_u64 v[154:155], v[136:137], 0, v[0:1]
	s_nop 1
	s_waitcnt vmcnt(9)
	v_mov_b64_e32 v[20:21], v[98:99]
	v_mov_b64_e32 v[22:23], v[100:101]
	global_load_dwordx4 v[98:101], v[154:155], off offset:16
	ds_read_b128 v[24:27], v214
	ds_read_b128 v[28:31], v213
	s_nop 1
	s_waitcnt vmcnt(9)
	v_mov_b64_e32 v[32:33], v[102:103]
	v_mov_b64_e32 v[34:35], v[104:105]
	global_load_dwordx4 v[102:105], v[154:155], off offset:2064
	ds_read_b128 v[36:39], v215
	ds_read_b128 v[78:81], v213 offset:128
	ds_read_b128 v[40:43], v214 offset:64
	ds_read_b128 v[82:85], v213 offset:64
	s_waitcnt lgkmcnt(4)
	v_mfma_f32_16x16x32_bf16 v[24:27], v[24:27], v[28:31], 0
	v_lshl_add_u64 v[152:153], v[134:135], 0, v[0:1]
	ds_read_b128 v[44:47], v215 offset:64
	ds_read_b128 v[156:159], v213 offset:192
	s_nop 1
	s_waitcnt vmcnt(7)
	v_mov_b64_e32 v[168:169], v[114:115]
	v_mov_b64_e32 v[170:171], v[116:117]
	global_load_dwordx4 v[114:117], v[152:153], off offset:16
	s_waitcnt lgkmcnt(2)
	v_mfma_f32_16x16x32_bf16 v[90:93], v[40:43], v[82:85], v[24:27]
	v_add_u32_e32 v0, 0x11000, v187
	v_add_u32_e32 v1, 0x13000, v187
	s_nop 0
	v_cndmask_b32_e64 v228, v20, 0, s[6:7]
	ds_read_b128 v[24:27], v216
	v_mfma_f32_16x16x32_bf16 v[36:39], v[36:39], v[78:81], 0
	v_add_u32_e32 v20, 0x13080, v187
	v_cndmask_b32_e64 v130, v23, 0, s[6:7]
	v_cndmask_b32_e64 v151, v22, 0, s[6:7]
	s_waitcnt lgkmcnt(1)
	v_mfma_f32_16x16x32_bf16 v[86:89], v[44:47], v[156:159], v[36:39]
	s_nop 2
	ds_read_b128 v[36:39], v217
	ds_read_b128 v[40:43], v216 offset:64
	ds_read_b128 v[44:47], v217 offset:64
	ds_read_b128 v[54:57], v218
	ds_read_b128 v[58:61], v218 offset:64
	ds_read_b128 v[62:65], v219
	ds_read_b128 v[66:69], v219 offset:64
	ds_read_b128 v[160:163], v220
	ds_read_b128 v[164:167], v220 offset:64
	s_waitcnt lgkmcnt(9)
	v_mfma_f32_16x16x32_bf16 v[24:27], v[24:27], v[28:31], 0
	v_cndmask_b32_e64 v186, v21, 0, s[6:7]
	s_nop 0
	v_cndmask_b32_e64 v33, v33, 0, s[6:7]
	v_cndmask_b32_e64 v48, v35, 0, s[6:7]
	s_waitcnt lgkmcnt(7)
	v_mfma_f32_16x16x32_bf16 v[50:53], v[40:43], v[82:85], v[24:27]
	s_nop 2
	ds_read_b128 v[24:27], v221
	ds_read_b128 v[172:175], v221 offset:64
	s_nop 1
	s_waitcnt vmcnt(10)
; __device__ __forceinline__ void prep_rwkv_phase(const Params& p, LAS unsigned char* lds, int gw, int ngw, int wave, int lane) {
;     ...
;         f32x4 accD[4], accA[4];
; #pragma unroll
;         for (int i = 0; i < 4; ++i) {
;             accD[i] = (f32x4){0.f, 0.f, 0.f, 0.f}; accA[i] = accD[i];
; #pragma unroll
;             for (int ks = 0; ks < 2; ++ks) {
;                 const bf16x8 wd = *(const LAS bf16x8*)(WD + (i * 16 + fr) * 72 + ks * 32 + fq * 8), ad = *(const LAS bf16x8*)(act + fr * 264 + ks * 32 + fq * 8);
;                 accD[i] = __builtin_amdgcn_mfma_f32_16x16x32_bf16(wd, ad, accD[i], 0, 0, 0);
;                 const bf16x8 wa = *(const LAS bf16x8*)(WA + (i * 16 + fr) * 72 + ks * 32 + fq * 8), aa = *(const LAS bf16x8*)(act + fr * 264 + 64 + ks * 32 + fq * 8);
;                 accA[i] = __builtin_amdgcn_mfma_f32_16x16x32_bf16(wa, aa, accA[i], 0, 0, 0);
;             }
;         }
;         float nk = 0.f, sbr = 0.f, skr = 0.f, sbo = 0.f;
;         u32x4 kcs[2], kps[2];
; #pragma unroll
;         for (int hf = 0; hf < 2; ++hf) {
;             const int o_ = h * 64 + fq * 16 + hf * 8;
;             kcs[hf] = *(const u32x4*)(prow + 512 + o_); kps[hf] = *(const u32x4*)(pprev + 512 + o_); if (first) kps[hf] = (u32x4){0u, 0u, 0u, 0u};
;             const u32x4 kc = kcs[hf], kp = kps[hf];
; #pragma unroll
;             for (int i2 = 0; i2 < 2; ++i2) { const int c = h * 64 + (2 * hf + i2) * 16 + 4 * fq; const f32x4 muk = *(const LAS f32x4*)(PRM + 512 + c), kk4 = *(const LAS f32x4*)(PRM + 2560 + c);
; #pragma unroll
;                 for (int j = 0; j < 4; ++j) { const int e8 = i2 * 4 + j; const unsigned wc_ = kc[e8 >> 1], wp_ = kp[e8 >> 1];
;                     const float kcur = (e8 & 1) ? bfhi(wc_) : bflo(wc_), kprv = (e8 & 1) ? bfhi(wp_) : bflo(wp_); const float kr_ = (kcur + (kprv - kcur) * muk[j]) * kk4[j]; nk += kr_ * kr_; } }
;         }
;         nk += __shfl_xor(nk, 16); nk += __shfl_xor(nk, 32);
;         const float inv = 1.f / fmaxf(sqrtf(nk), 1e-12f);
;         h16* scp = SC + ((size_t)(b * 8 + h) * SEQ + tin) * 384 + fq * 16;
; #pragma unroll
;         for (int hf = 0; hf < 2; ++hf) {
;             h16x8 owr, odec, ok2, ov, okk, ob;
;             const int o_ = h * 64 + fq * 16 + hf * 8;
;             const u32x4 rc = *(const u32x4*)(prow + o_), kc = kcs[hf], vc = *(const u32x4*)(prow + 1024 + o_);
	v_mov_b64_e32 v[176:177], v[106:107]
	v_mov_b64_e32 v[178:179], v[108:109]
	global_load_dwordx4 v[106:109], v[152:153], off offset:2064
	s_nop 1
	s_waitcnt vmcnt(10)
	v_mov_b64_e32 v[180:181], v[110:111]
	v_mov_b64_e32 v[182:183], v[112:113]
	v_mfma_f32_16x16x32_bf16 v[36:39], v[36:39], v[78:81], 0
	s_nop 0
	v_and_b32_e32 v132, 0xffff0000, v171
	v_lshlrev_b32_e32 v185, 16, v168
	s_nop 0
	v_cndmask_b32_e64 v239, v182, 0, s[6:7]
	s_waitcnt lgkmcnt(8)
	v_mfma_f32_16x16x32_bf16 v[74:77], v[44:47], v[156:159], v[36:39]
	v_cndmask_b32_e64 v182, v181, 0, s[6:7]
	v_cndmask_b32_e64 v238, v183, 0, s[6:7]
	s_waitcnt lgkmcnt(7)
	v_mfma_f32_16x16x32_bf16 v[44:47], v[54:57], v[28:31], 0
	v_add_u32_e32 v36, 0x13040, v187
	s_waitcnt lgkmcnt(5)
	v_mfma_f32_16x16x32_bf16 v[70:73], v[62:65], v[78:81], 0
	ds_read_b128 v[188:191], v0
	ds_read_b128 v[40:43], v1
	ds_read_b128 v[62:65], v2
	ds_read_b128 v[36:39], v36
	v_add_u32_e32 v1, 0x11080, v187
	v_cndmask_b32_e64 v0, v32, 0, s[6:7]
	v_mfma_f32_16x16x32_bf16 v[54:57], v[58:61], v[82:85], v[44:47]
	v_lshlrev_b32_e32 v184, 16, v0
	v_and_b32_e32 v0, 0xffff0000, v0
	v_cndmask_b32_e64 v2, v34, 0, s[6:7]
	s_waitcnt lgkmcnt(8)
	v_mfma_f32_16x16x32_bf16 v[58:61], v[66:69], v[156:159], v[70:73]
	s_nop 2
	ds_read_b128 v[70:73], v1
	ds_read_b128 v[44:47], v20
	s_nop 1
	s_waitcnt vmcnt(8)
	v_mov_b64_e32 v[66:67], v[122:123]
	v_mov_b64_e32 v[68:69], v[124:125]
	v_and_b32_e32 v1, 0xffff0000, v169
	s_waitcnt lgkmcnt(9)
	v_mfma_f32_16x16x32_bf16 v[20:23], v[160:163], v[28:31], 0
	v_and_b32_e32 v161, 0xffff0000, v168
	v_sub_f32_e32 v0, v0, v161
	s_waitcnt lgkmcnt(1)
	v_fmac_f32_e32 v161, v71, v0
	v_mfma_f32_16x16x32_bf16 v[28:31], v[24:27], v[78:81], 0
	v_lshlrev_b32_e32 v0, 16, v169
	v_cndmask_b32_e64 v160, v177, 0, s[6:7]
	v_cndmask_b32_e64 v71, v178, 0, s[6:7]
	v_mfma_f32_16x16x32_bf16 v[24:27], v[164:167], v[82:85], v[20:23]
	s_nop 1
	s_waitcnt vmcnt(7)
	v_mov_b64_e32 v[78:79], v[126:127]
	v_mov_b64_e32 v[80:81], v[128:129]
	s_nop 1
	s_waitcnt vmcnt(6)
	v_mov_b64_e32 v[82:83], v[240:241]
	v_mov_b64_e32 v[84:85], v[242:243]
	s_nop 0
	v_and_b32_e32 v21, 0xffff0000, v33
	v_lshlrev_b32_e32 v20, 16, v33
	v_pk_add_f32 v[20:21], v[20:21], v[0:1] neg_lo:[0,1] neg_hi:[0,1]
	v_mfma_f32_16x16x32_bf16 v[28:31], v[172:175], v[156:159], v[28:31]
	v_fma_f32 v162, v72, v20, v0
	v_fma_f32 v163, v73, v21, v1
	v_add_u32_e32 v0, 0x110c0, v187
	v_add_u32_e32 v1, 0x130c0, v187
	ds_read_b128 v[32:35], v0
	ds_read_b128 v[20:23], v1
	s_waitcnt lgkmcnt(2)
	v_pk_mul_f32 v[158:159], v[46:47], v[162:163]
	v_and_b32_e32 v1, 0xffff0000, v170
	v_lshlrev_b32_e32 v0, 16, v170
	v_and_b32_e32 v47, 0xffff0000, v2
	v_lshlrev_b32_e32 v46, 16, v2
	v_pk_add_f32 v[46:47], v[46:47], v[0:1] neg_lo:[0,1] neg_hi:[0,1]
	v_lshlrev_b32_e32 v172, 16, v171
	s_waitcnt lgkmcnt(1)
	v_pk_fma_f32 v[164:165], v[32:33], v[46:47], v[0:1]
	v_lshlrev_b32_e32 v0, 16, v48
	v_sub_f32_e32 v0, v0, v172
	v_add_u32_e32 v32, 0x12000, v187
	v_mul_f32_e32 v150, v34, v0
	v_and_b32_e32 v0, 0xffff0000, v48
	ds_read_b128 v[46:49], v32
	v_add_u32_e32 v34, 0x12800, v187
	v_cndmask_b32_e64 v173, v176, 0, s[6:7]
	ds_read_b128 v[174:177], v34
	v_add_u32_e32 v32, 0x10800, v187
	s_waitcnt lgkmcnt(1)
	v_add_f32_e32 v34, v90, v46
	v_mul_f32_e32 v34, 0xbfb8aa3b, v34
	v_exp_f32_e32 v34, v34
	v_add_u32_e32 v33, 0x11800, v187
	ds_read_b128 v[192:195], v32
	ds_read_b128 v[196:199], v33
	s_waitcnt lgkmcnt(2)
	v_add_f32_e32 v72, v86, v174
	v_add_f32_e32 v33, 1.0, v34
	v_rcp_f32_e32 v46, v33
	v_mul_f32_e32 v72, 0xbfb8aa3b, v72
	v_add_f32_e32 v47, v91, v47
	v_exp_f32_e32 v72, v72
	v_mul_f32_e32 v47, 0xbfb8aa3b, v47
	v_exp_f32_e32 v47, v47
	v_mul_f32_e32 v46, 0xbf1b4598, v46
	v_mul_f32_e32 v46, 0x3fb8aa3b, v46
	v_cndmask_b32_e64 v73, v180, 0, s[6:7]
	v_exp_f32_e32 v180, v46
	v_add_f32_e32 v46, 1.0, v72
	v_rcp_f32_e32 v170, v46
	v_add_f32_e32 v46, 1.0, v47
	v_rcp_f32_e32 v46, v46
	v_add_f32_e32 v47, v87, v175
	v_mul_f32_e32 v47, 0xbfb8aa3b, v47
	v_exp_f32_e32 v47, v47
	v_mul_f32_e32 v46, 0xbf1b4598, v46
	v_mul_f32_e32 v46, 0x3fb8aa3b, v46
	v_exp_f32_e32 v181, v46
	v_add_f32_e32 v46, 1.0, v47
	v_rcp_f32_e32 v171, v46
	v_lshlrev_b32_e32 v72, 16, v73
	v_and_b32_e32 v73, 0xffff0000, v73
	v_sub_f32_e32 v0, v0, v132
	v_add_u32_e32 v32, 0x13800, v187
	v_add_u32_e32 v33, 0x14000, v187
	v_pk_mul_f32 v[156:157], v[20:21], v[164:165]
	v_mul_f32_e32 v20, v35, v0
	ds_read_b128 v[200:203], v32
	ds_read_b128 v[32:35], v33
	v_lshlrev_b32_e32 v90, 16, v228
	v_and_b32_e32 v91, 0xffff0000, v228
	v_cndmask_b32_e64 v21, v179, 0, s[6:7]
	v_lshlrev_b32_e32 v174, 16, v173
	v_and_b32_e32 v175, 0xffff0000, v173
	v_and_b32_e32 v1, 64, v227
	v_xor_b32_e32 v0, 16, v227
	v_add_u32_e32 v1, 64, v1
	v_cmp_lt_i32_e32 vcc, v0, v1
	v_pk_mul_f32 v[166:167], v[158:159], v[158:159]
	v_mov_b32_e32 v173, v133
	v_cndmask_b32_e32 v0, v227, v0, vcc
	v_lshlrev_b32_e32 v145, 2, v0
	v_xor_b32_e32 v0, 32, v227
	v_cmp_lt_i32_e32 vcc, v0, v1
	s_nop 0
	v_lshlrev_b32_e32 v46, 16, v82
	v_and_b32_e32 v47, 0xffff0000, v82
	v_pk_add_f32 v[72:73], v[72:73], v[46:47] neg_lo:[0,1] neg_hi:[0,1]
	v_cndmask_b32_e32 v0, v227, v0, vcc
	s_waitcnt lgkmcnt(3)
	v_pk_fma_f32 v[86:87], v[192:193], v[72:73], v[46:47]
	v_lshlrev_b32_e32 v2, 2, v0
	v_pk_mul_f32 v[46:47], v[86:87], v[180:181]
	v_lshl_add_u64 v[0:1], s[92:93], 0, v[140:141]
	v_cvt_pk_f16_f32 v72, v46, v47
	v_lshlrev_b32_e32 v46, 16, v78
	v_and_b32_e32 v47, 0xffff0000, v78
	v_pk_add_f32 v[90:91], v[90:91], v[46:47] neg_lo:[0,1] neg_hi:[0,1]
	v_pk_mul_f32 v[168:169], v[156:157], v[156:157]
	v_pk_fma_f32 v[178:179], v[188:189], v[90:91], v[46:47]
	v_pk_add_f32 v[46:47], v[170:171], -1.0 op_sel_hi:[1,0]
	s_waitcnt lgkmcnt(1)
; #define LAS __attribute__((address_space(3)))
; __device__ __forceinline__ float fast_sigmoid(float x) { return __builtin_amdgcn_rcpf(1.f + __expf(-x)); }
; __device__ __forceinline__ void prep_rwkv_phase(const Params& p, LAS unsigned char* lds, int gw, int ngw, int wave, int lane) {
;     ...
;         for (int hf = 0; hf < 2; ++hf) {
;             h16x8 owr, odec, ok2, ov, okk, ob;
;             const int o_ = h * 64 + fq * 16 + hf * 8;
;             const u32x4 rc = *(const u32x4*)(prow + o_), kc = kcs[hf], vc = *(const u32x4*)(prow + 1024 + o_);
;             u32x4 rp = *(const u32x4*)(pprev + o_), vp = *(const u32x4*)(pprev + 1024 + o_); const u32x4 kp = kps[hf];
;             if (first) { rp = (u32x4){0u, 0u, 0u, 0u}; vp = rp; }
; #pragma unroll
;             for (int i2 = 0; i2 < 2; ++i2) {
;                 const int i = 2 * hf + i2, c = h * 64 + i * 16 + 4 * fq;
;                 const f32x4 mur = *(const LAS f32x4*)(PRM + c), muk = *(const LAS f32x4*)(PRM + 512 + c), muv = *(const LAS f32x4*)(PRM + 1024 + c);
;                 const f32x4 w04 = *(const LAS f32x4*)(PRM + 1536 + c), a04 = *(const LAS f32x4*)(PRM + 2048 + c), kk4 = *(const LAS f32x4*)(PRM + 2560 + c), ka4 = *(const LAS f32x4*)(PRM + 3072 + c), rk4 = *(const LAS f32x4*)(PRM + 3584 + c);
; #pragma unroll
;                 for (int j = 0; j < 4; ++j) {
;                     const int e8 = i2 * 4 + j, e = hf * 8 + e8; const unsigned wsel = (e8 >> 1); const bool hiw = e8 & 1;
;     ...
;                     const float rcur = PREP_GET(rc), rprv = PREP_GET(rp), kcur = PREP_GET(kc), kprv = PREP_GET(kp), vcur = PREP_GET(vc), vprv = PREP_GET(vp);
;     ...
;                     const float r = rcur + (rprv - rcur) * mur[j], k = kcur + (kprv - kcur) * muk[j], v = vcur + (vprv - vcur) * muv[j];
;                     const float dec = __expf(-0.60653066f * fast_sigmoid(w04[j] + accD[i][j]));
;                     const float a = fast_sigmoid(a04[j] + accA[i][j]);
;                     const float kraw = k * kk4[j], k2 = k * (1.f + (a - 1.f) * ka4[j]);
;                     const float kkn = kraw * inv, bn = kkn * a; sbr += bn * r; skr += k2 * r; sbo += r * k2 * rk4[j];
;                     okk[e8] = (h16)kkn; ob[e8] = (h16)bn;
;                     owr[e8] = (h16)(dec * r); odec[e8] = (h16)dec; ok2[e8] = (h16)k2; ov[e8] = (h16)v;
;                 }
;             }
	v_pk_fma_f32 v[46:47], v[200:201], v[46:47], 1.0 op_sel_hi:[1,1,0]
	s_nop 0
	v_pk_mul_f32 v[90:91], v[178:179], v[46:47]
	v_add_f32_e32 v47, v92, v48
	v_mul_f32_e32 v47, 0xbfb8aa3b, v47
	v_exp_f32_e32 v48, v47
	v_lshlrev_b32_e32 v46, 16, v66
	v_and_b32_e32 v47, 0xffff0000, v66
	v_pk_add_f32 v[174:175], v[174:175], v[46:47] neg_lo:[0,1] neg_hi:[0,1]
	v_add_f32_e32 v48, 1.0, v48
	v_rcp_f32_e32 v48, v48
	v_pk_fma_f32 v[46:47], v[196:197], v[174:175], v[46:47]
	v_lshlrev_b32_e32 v174, 16, v80
	v_cvt_pk_f16_f32 v66, v46, v47
	v_add_f32_e32 v47, v88, v176
	v_mul_f32_e32 v46, 0xbf1b4598, v48
	v_mul_f32_e32 v47, 0xbfb8aa3b, v47
	v_add_f32_e32 v48, v93, v49
	v_exp_f32_e32 v47, v47
	v_mul_f32_e32 v48, 0xbfb8aa3b, v48
	v_exp_f32_e32 v48, v48
	v_mul_f32_e32 v46, 0x3fb8aa3b, v46
	v_exp_f32_e32 v236, v46
	v_add_f32_e32 v46, 1.0, v47
	v_rcp_f32_e32 v176, v46
	v_add_f32_e32 v46, 1.0, v48
	v_rcp_f32_e32 v46, v46
	v_add_f32_e32 v47, v89, v177
	v_mul_f32_e32 v47, 0xbfb8aa3b, v47
	v_exp_f32_e32 v47, v47
	v_mul_f32_e32 v46, 0xbf1b4598, v46
	v_mul_f32_e32 v46, 0x3fb8aa3b, v46
	v_exp_f32_e32 v237, v46
	v_add_f32_e32 v46, 1.0, v47
	v_rcp_f32_e32 v177, v46
	v_lshlrev_b32_e32 v46, 16, v83
	v_and_b32_e32 v47, 0xffff0000, v83
	v_lshlrev_b32_e32 v48, 16, v182
	v_and_b32_e32 v49, 0xffff0000, v182
	v_pk_add_f32 v[48:49], v[48:49], v[46:47] neg_lo:[0,1] neg_hi:[0,1]
	v_and_b32_e32 v175, 0xffff0000, v80
	v_pk_fma_f32 v[82:83], v[194:195], v[48:49], v[46:47]
	v_lshlrev_b32_e32 v48, 16, v186
	v_pk_mul_f32 v[46:47], v[82:83], v[236:237]
	v_and_b32_e32 v49, 0xffff0000, v186
	v_cvt_pk_f16_f32 v73, v46, v47
	v_lshlrev_b32_e32 v46, 16, v79
	v_and_b32_e32 v47, 0xffff0000, v79
	v_pk_add_f32 v[48:49], v[48:49], v[46:47] neg_lo:[0,1] neg_hi:[0,1]
	v_lshlrev_b32_e32 v92, 16, v239
	v_pk_fma_f32 v[188:189], v[190:191], v[48:49], v[46:47]
	v_pk_add_f32 v[46:47], v[176:177], -1.0 op_sel_hi:[1,0]
	v_lshlrev_b32_e32 v48, 16, v160
	v_pk_fma_f32 v[46:47], v[202:203], v[46:47], 1.0 op_sel_hi:[1,1,0]
	v_and_b32_e32 v49, 0xffff0000, v160
	v_pk_mul_f32 v[88:89], v[188:189], v[46:47]
	v_lshlrev_b32_e32 v46, 16, v67
	v_and_b32_e32 v47, 0xffff0000, v67
	v_pk_add_f32 v[48:49], v[48:49], v[46:47] neg_lo:[0,1] neg_hi:[0,1]
	v_and_b32_e32 v93, 0xffff0000, v239
	v_pk_fma_f32 v[46:47], v[198:199], v[48:49], v[46:47]
	v_add_u32_e32 v48, 0x12840, v187
	v_cvt_pk_f16_f32 v67, v46, v47
	v_add_u32_e32 v46, 0x12040, v187
	ds_read_b128 v[190:193], v46
	ds_read_b128 v[194:197], v48
	v_add_u32_e32 v46, 0x10840, v187
	v_add_u32_e32 v47, 0x11840, v187
	ds_read_b128 v[198:201], v46
	ds_read_b128 v[228:231], v47
	s_waitcnt lgkmcnt(3)
	v_add_f32_e32 v48, v50, v190
	s_waitcnt lgkmcnt(2)
	v_add_f32_e32 v74, v74, v194
	v_mul_f32_e32 v74, 0xbfb8aa3b, v74
	v_exp_f32_e32 v74, v74
	v_mul_f32_e32 v48, 0xbfb8aa3b, v48
	v_exp_f32_e32 v48, v48
	v_add_u32_e32 v46, 0x13840, v187
	v_add_f32_e32 v74, 1.0, v74
	v_rcp_f32_e32 v182, v74
	v_add_f32_e32 v74, v75, v195
	v_mul_f32_e32 v74, 0xbfb8aa3b, v74
	v_exp_f32_e32 v74, v74
	v_add_f32_e32 v47, 1.0, v48
	v_rcp_f32_e32 v50, v47
	v_add_u32_e32 v47, 0x14040, v187
	v_add_f32_e32 v74, 1.0, v74
	v_rcp_f32_e32 v183, v74
	ds_read_b128 v[232:235], v46
	ds_read_b128 v[46:49], v47
	v_add_f32_e32 v51, v51, v191
	v_lshlrev_b32_e32 v190, 16, v151
	v_and_b32_e32 v191, 0xffff0000, v151
	v_pk_add_f32 v[190:191], v[190:191], v[174:175] neg_lo:[0,1] neg_hi:[0,1]
	v_add_f32_e32 v52, v52, v192
	v_pk_fma_f32 v[202:203], v[62:63], v[190:191], v[174:175]
	v_pk_add_f32 v[62:63], v[182:183], -1.0 op_sel_hi:[1,0]
	v_lshlrev_b32_e32 v190, 16, v71
	s_waitcnt lgkmcnt(1)
	v_pk_fma_f32 v[62:63], v[232:233], v[62:63], 1.0 op_sel_hi:[1,1,0]
	v_and_b32_e32 v191, 0xffff0000, v71
	v_pk_mul_f32 v[174:175], v[202:203], v[62:63]
	v_lshlrev_b32_e32 v62, 16, v68
	v_and_b32_e32 v63, 0xffff0000, v68
	v_pk_add_f32 v[190:191], v[190:191], v[62:63] neg_lo:[0,1] neg_hi:[0,1]
	v_add_f32_e32 v53, v53, v193
	v_pk_fma_f32 v[62:63], v[190:191], v[228:229], v[62:63]
	v_mul_f32_e32 v51, 0xbfb8aa3b, v51
	v_cvt_pk_f16_f32 v68, v62, v63
	v_add_f32_e32 v62, v76, v196
	v_mul_f32_e32 v52, 0xbfb8aa3b, v52
	v_mul_f32_e32 v62, 0xbfb8aa3b, v62
	v_mul_f32_e32 v53, 0xbfb8aa3b, v53
	v_exp_f32_e32 v51, v51
	v_exp_f32_e32 v52, v52
	v_exp_f32_e32 v62, v62
	v_exp_f32_e32 v53, v53
	v_add_f32_e32 v51, 1.0, v51
	v_add_f32_e32 v52, 1.0, v52
	v_add_f32_e32 v62, 1.0, v62
	v_add_f32_e32 v53, 1.0, v53
	v_rcp_f32_e32 v51, v51
	v_rcp_f32_e32 v52, v52
	v_rcp_f32_e32 v196, v62
	v_rcp_f32_e32 v53, v53
	v_add_f32_e32 v62, v77, v197
	v_mul_f32_e32 v62, 0xbfb8aa3b, v62
	v_exp_f32_e32 v62, v62
	v_mul_f32_e32 v50, 0xbf1b4598, v50
	v_mul_f32_e32 v51, 0xbf1b4598, v51
	v_mul_f32_e32 v52, 0xbf1b4598, v52
	v_mul_f32_e32 v53, 0xbf1b4598, v53
	v_mul_f32_e32 v50, 0x3fb8aa3b, v50
	v_mul_f32_e32 v51, 0x3fb8aa3b, v51
	v_mul_f32_e32 v52, 0x3fb8aa3b, v52
	v_mul_f32_e32 v53, 0x3fb8aa3b, v53
	v_exp_f32_e32 v50, v50
	v_exp_f32_e32 v51, v51
	v_exp_f32_e32 v52, v52
	v_exp_f32_e32 v53, v53
	v_add_f32_e32 v62, 1.0, v62
	v_lshlrev_b32_e32 v74, 16, v84
	v_and_b32_e32 v75, 0xffff0000, v84
	v_rcp_f32_e32 v197, v62
	v_lshlrev_b32_e32 v62, 16, v85
	v_and_b32_e32 v63, 0xffff0000, v85
	v_lshlrev_b32_e32 v76, 16, v238
	v_and_b32_e32 v77, 0xffff0000, v238
	v_pk_add_f32 v[92:93], v[92:93], v[74:75] neg_lo:[0,1] neg_hi:[0,1]
	v_pk_add_f32 v[76:77], v[76:77], v[62:63] neg_lo:[0,1] neg_hi:[0,1]
	v_pk_fma_f32 v[92:93], v[92:93], v[198:199], v[74:75]
	v_pk_fma_f32 v[84:85], v[76:77], v[200:201], v[62:63]
	v_pk_mul_f32 v[74:75], v[92:93], v[50:51]
	v_pk_mul_f32 v[62:63], v[84:85], v[52:53]
	v_cvt_pk_f16_f32 v74, v74, v75
	v_cvt_pk_f16_f32 v75, v62, v63
	v_lshlrev_b32_e32 v62, 16, v81
	v_and_b32_e32 v63, 0xffff0000, v81
	v_lshlrev_b32_e32 v76, 16, v130
	v_and_b32_e32 v77, 0xffff0000, v130
	v_pk_add_f32 v[76:77], v[76:77], v[62:63] neg_lo:[0,1] neg_hi:[0,1]
	v_cvt_pk_f16_f32 v53, v52, v53
	v_pk_fma_f32 v[232:233], v[64:65], v[76:77], v[62:63]
	v_pk_add_f32 v[62:63], v[196:197], -1.0 op_sel_hi:[1,0]
	v_cvt_pk_f16_f32 v52, v50, v51
	v_pk_fma_f32 v[62:63], v[234:235], v[62:63], 1.0 op_sel_hi:[1,1,0]
	v_cvt_pk_f16_f32 v50, v180, v181
	v_pk_mul_f32 v[180:181], v[232:233], v[62:63]
	v_lshlrev_b32_e32 v62, 16, v69
	v_and_b32_e32 v63, 0xffff0000, v69
	v_lshlrev_b32_e32 v64, 16, v21
	v_and_b32_e32 v65, 0xffff0000, v21
	v_pk_add_f32 v[64:65], v[64:65], v[62:63] neg_lo:[0,1] neg_hi:[0,1]
	v_cvt_pk_f16_f32 v78, v90, v91
	v_pk_fma_f32 v[62:63], v[64:65], v[230:231], v[62:63]
	v_cvt_pk_f16_f32 v79, v88, v89
	v_cvt_pk_f16_f32 v80, v174, v175
	v_cvt_pk_f16_f32 v51, v236, v237
	v_cvt_pk_f16_f32 v81, v180, v181
	v_cvt_pk_f16_f32 v69, v62, v63
	global_store_dwordx4 v[0:1], v[72:75], off offset:-256
	global_store_dwordx4 v[0:1], v[50:53], off offset:-128
	global_store_dwordx4 v[0:1], v[78:81], off offset:128
	global_store_dwordx4 v[0:1], v[66:69], off offset:256
	v_add_u32_e32 v21, 0x12080, v187
	ds_read_b128 v[72:75], v21
	v_add_u32_e32 v51, 0x12880, v187
	ds_read_b128 v[78:81], v51
	v_add_u32_e32 v21, 0x10880, v187
	v_add_u32_e32 v50, 0x11880, v187
	s_waitcnt lgkmcnt(1)
; __device__ __forceinline__ void prep_rwkv_phase(const Params& p, LAS unsigned char* lds, int gw, int ngw, int wave, int lane) {
;     ...
;         float nk = 0.f, sbr = 0.f, skr = 0.f, sbo = 0.f;
;         u32x4 kcs[2], kps[2];
; #pragma unroll
;         for (int hf = 0; hf < 2; ++hf) {
;             const int o_ = h * 64 + fq * 16 + hf * 8;
;             kcs[hf] = *(const u32x4*)(prow + 512 + o_); kps[hf] = *(const u32x4*)(pprev + 512 + o_); if (first) kps[hf] = (u32x4){0u, 0u, 0u, 0u};
;             const u32x4 kc = kcs[hf], kp = kps[hf];
; #pragma unroll
;             for (int i2 = 0; i2 < 2; ++i2) { const int c = h * 64 + (2 * hf + i2) * 16 + 4 * fq; const f32x4 muk = *(const LAS f32x4*)(PRM + 512 + c), kk4 = *(const LAS f32x4*)(PRM + 2560 + c);
; #pragma unroll
;                 for (int j = 0; j < 4; ++j) { const int e8 = i2 * 4 + j; const unsigned wc_ = kc[e8 >> 1], wp_ = kp[e8 >> 1];
;                     const float kcur = (e8 & 1) ? bfhi(wc_) : bflo(wc_), kprv = (e8 & 1) ? bfhi(wp_) : bflo(wp_); const float kr_ = (kcur + (kprv - kcur) * muk[j]) * kk4[j]; nk += kr_ * kr_; } }
;         }
;         nk += __shfl_xor(nk, 16); nk += __shfl_xor(nk, 32);
;         const float inv = 1.f / fmaxf(sqrtf(nk), 1e-12f);
;         h16* scp = SC + ((size_t)(b * 8 + h) * SEQ + tin) * 384 + fq * 16;
; #pragma unroll
;         for (int hf = 0; hf < 2; ++hf) {
;             h16x8 owr, odec, ok2, ov, okk, ob;
;             const int o_ = h * 64 + fq * 16 + hf * 8;
;             const u32x4 rc = *(const u32x4*)(prow + o_), kc = kcs[hf], vc = *(const u32x4*)(prow + 1024 + o_);
;             u32x4 rp = *(const u32x4*)(pprev + o_), vp = *(const u32x4*)(pprev + 1024 + o_); const u32x4 kp = kps[hf];
;             if (first) { rp = (u32x4){0u, 0u, 0u, 0u}; vp = rp; }
; #pragma unroll
;             for (int i2 = 0; i2 < 2; ++i2) {
;                 const int i = 2 * hf + i2, c = h * 64 + i * 16 + 4 * fq;
;                 const f32x4 mur = *(const LAS f32x4*)(PRM + c), muk = *(const LAS f32x4*)(PRM + 512 + c), muv = *(const LAS f32x4*)(PRM + 1024 + c);
;                 const f32x4 w04 = *(const LAS f32x4*)(PRM + 1536 + c), a04 = *(const LAS f32x4*)(PRM + 2048 + c), kk4 = *(const LAS f32x4*)(PRM + 2560 + c), ka4 = *(const LAS f32x4*)(PRM + 3072 + c), rk4 = *(const LAS f32x4*)(PRM + 3584 + c);
; #pragma unroll
;                 for (int j = 0; j < 4; ++j) {
	v_add_f32_e32 v51, v54, v72
	v_mul_f32_e32 v51, 0xbfb8aa3b, v51
	v_exp_f32_e32 v54, v51
	s_waitcnt lgkmcnt(0)
	v_add_f32_e32 v58, v58, v78
	v_mul_f32_e32 v58, 0xbfb8aa3b, v58
	v_exp_f32_e32 v58, v58
	v_add_f32_e32 v54, 1.0, v54
	v_rcp_f32_e32 v54, v54
	ds_read_b128 v[62:65], v21
	ds_read_b128 v[50:53], v50
	v_add_u32_e32 v21, 0x13880, v187
	v_add_u32_e32 v66, 0x14080, v187
	ds_read_b128 v[228:231], v21
	ds_read_b128 v[66:69], v66
	v_add_f32_e32 v21, 1.0, v58
	v_rcp_f32_e32 v186, v21
	v_mul_f32_e32 v21, 0xbf1b4598, v54
	v_mov_b32_e32 v54, v185
	v_pk_add_f32 v[76:77], v[184:185], v[54:55] neg_lo:[0,1] neg_hi:[0,1]
	v_add_f32_e32 v54, v59, v79
	v_mul_f32_e32 v21, 0x3fb8aa3b, v21
	v_mul_f32_e32 v54, 0xbfb8aa3b, v54
	v_exp_f32_e32 v78, v21
	v_add_f32_e32 v21, -1.0, v186
	v_exp_f32_e32 v54, v54
	v_mov_b32_e32 v77, v21
	v_add_f32_e32 v21, v55, v73
	v_mul_f32_e32 v21, 0xbfb8aa3b, v21
	v_exp_f32_e32 v21, v21
	v_add_f32_e32 v54, 1.0, v54
	v_rcp_f32_e32 v160, v54
	v_add_f32_e32 v54, v56, v74
	v_mul_f32_e32 v54, 0xbfb8aa3b, v54
	v_add_f32_e32 v21, 1.0, v21
	v_exp_f32_e32 v54, v54
	v_rcp_f32_e32 v21, v21
	v_add_f32_e32 v55, v60, v80
	v_mul_f32_e32 v55, 0xbfb8aa3b, v55
	v_exp_f32_e32 v55, v55
	v_add_f32_e32 v54, 1.0, v54
	v_mul_f32_e32 v21, 0xbf1b4598, v21
	v_rcp_f32_e32 v54, v54
	v_mul_f32_e32 v21, 0x3fb8aa3b, v21
	v_exp_f32_e32 v79, v21
	v_add_f32_e32 v21, -1.0, v160
	s_waitcnt lgkmcnt(1)
	v_fma_f32 v201, v229, v21, 1.0
	v_add_f32_e32 v21, 1.0, v55
	v_rcp_f32_e32 v184, v21
	v_mul_f32_e32 v21, 0xbf1b4598, v54
	v_add_f32_e32 v54, v57, v75
	v_mul_f32_e32 v54, 0xbfb8aa3b, v54
	v_exp_f32_e32 v54, v54
	v_add_f32_e32 v55, v61, v81
	v_mul_f32_e32 v55, 0xbfb8aa3b, v55
	v_exp_f32_e32 v55, v55
	v_add_f32_e32 v54, 1.0, v54
	v_rcp_f32_e32 v54, v54
	v_mul_f32_e32 v21, 0x3fb8aa3b, v21
	v_exp_f32_e32 v80, v21
	v_add_f32_e32 v21, -1.0, v184
	v_fma_f32 v195, v230, v21, 1.0
	v_add_f32_e32 v21, 1.0, v55
	v_rcp_f32_e32 v190, v21
	v_mul_f32_e32 v21, 0xbf1b4598, v54
	v_mul_f32_e32 v21, 0x3fb8aa3b, v21
	v_mov_b32_e32 v71, v228
	v_mov_b32_e32 v130, v185
	v_exp_f32_e32 v81, v21
	v_add_u32_e32 v21, 0x120c0, v187
	v_pk_fma_f32 v[192:193], v[70:71], v[76:77], v[130:131]
	v_add_u32_e32 v54, 0x128c0, v187
	ds_read_b128 v[70:73], v21
	ds_read_b128 v[74:77], v54
	v_add_u32_e32 v21, 0x138c0, v187
	v_add_u32_e32 v54, 0x140c0, v187
	ds_read_b128 v[58:61], v21
	ds_read_b128 v[54:57], v54
	s_waitcnt lgkmcnt(3)
	v_add_f32_e32 v21, v24, v70
	v_mul_f32_e32 v24, 0xbfb8aa3b, v21
	s_waitcnt lgkmcnt(2)
	v_add_f32_e32 v21, v31, v77
	v_add_f32_e32 v30, v30, v76
	v_pk_mul_f32 v[228:229], v[40:41], v[178:179]
	v_mul_f32_e32 v21, 0xbfb8aa3b, v21
	v_mul_f32_e32 v30, 0xbfb8aa3b, v30
	v_pk_mul_f32 v[40:41], v[228:229], v[228:229]
	v_pk_mul_f32 v[188:189], v[42:43], v[188:189]
	v_exp_f32_e32 v21, v21
	v_exp_f32_e32 v30, v30
	v_pk_mul_f32 v[42:43], v[188:189], v[188:189]
	v_add_f32_e32 v40, v40, v41
	v_pk_mul_f32 v[202:203], v[36:37], v[202:203]
	v_add_f32_e32 v40, v42, v40
	v_pk_mul_f32 v[36:37], v[202:203], v[202:203]
	v_add_f32_e32 v40, v43, v40
	v_pk_mul_f32 v[232:233], v[38:39], v[232:233]
	v_add_f32_e32 v36, v36, v40
	v_add_f32_e32 v21, 1.0, v21
	v_add_f32_e32 v30, 1.0, v30
	v_pk_mul_f32 v[38:39], v[232:233], v[232:233]
	v_mov_b32_e32 v178, v192
	v_mov_b32_e32 v179, v161
	v_add_f32_e32 v36, v37, v36
	v_rcp_f32_e32 v21, v21
	v_rcp_f32_e32 v151, v30
	v_pk_mul_f32 v[178:179], v[44:45], v[178:179]
	v_add_f32_e32 v36, v38, v36
	v_pk_mul_f32 v[234:235], v[178:179], v[178:179]
	v_add_f32_e32 v36, v39, v36
	v_add_f32_e32 v36, v234, v36
	v_add_f32_e32 v36, v235, v36
	v_pk_add_f32 v[30:31], v[20:21], v[132:133]
	v_mov_b32_e32 v76, v23
	s_waitcnt lgkmcnt(1)
	v_mov_b32_e32 v77, v61
	v_pk_add_f32 v[44:45], v[150:151], v[172:173]
	v_mov_b32_e32 v23, v60
	v_add_f32_e32 v36, v166, v36
	v_pk_mul_f32 v[198:199], v[76:77], v[30:31]
	v_pk_mul_f32 v[60:61], v[22:23], v[44:45]
	v_add_f32_e32 v36, v167, v36
	v_mov_b32_e32 v172, v198
	v_mov_b32_e32 v173, v60
	v_add_f32_e32 v36, v168, v36
	v_pk_mul_f32 v[172:173], v[172:173], v[172:173]
	v_add_f32_e32 v36, v169, v36
	v_add_f32_e32 v36, v173, v36
	v_add_f32_e32 v36, v172, v36
	ds_bpermute_b32 v37, v145, v36
	v_exp_f32_e32 v24, v24
	v_add_f32_e32 v28, v28, v74
	v_mul_f32_e32 v28, 0xbfb8aa3b, v28
	v_exp_f32_e32 v28, v28
	s_waitcnt lgkmcnt(0)
	v_add_f32_e32 v36, v36, v37
	ds_bpermute_b32 v37, v2, v36
	v_add_f32_e32 v24, 1.0, v24
	v_rcp_f32_e32 v24, v24
	v_add_f32_e32 v130, -1.0, v190
	v_fma_f32 v167, v231, v130, 1.0
	s_waitcnt lgkmcnt(0)
	v_add_f32_e32 v36, v36, v37
	v_mul_f32_e32 v37, 0x4f800000, v36
	v_cmp_gt_f32_e32 vcc, s29, v36
	v_mul_f32_e32 v132, 0xbf1b4598, v24
	v_add_f32_e32 v24, 1.0, v28
	v_cndmask_b32_e32 v70, v36, v37, vcc
	v_sqrt_f32_e32 v74, v70
	v_add_u32_e32 v38, 0x108c0, v187
	v_add_u32_e32 v39, 0x118c0, v187
	ds_read_b128 v[40:43], v38
	ds_read_b128 v[36:39], v39
	v_add_u32_e32 v28, -1, v74
	v_fma_f32 v130, -v28, v74, v70
	v_cmp_ge_f32_e64 s[8:9], 0, v130
	v_add_u32_e32 v130, 1, v74
	v_add_f32_e32 v26, v26, v72
	v_cndmask_b32_e64 v28, v74, v28, s[8:9]
	v_fma_f32 v74, -v130, v74, v70
	v_cmp_lt_f32_e64 s[8:9], 0, v74
	v_add_f32_e32 v27, v27, v73
	v_mov_b32_e32 v185, v162
	v_cndmask_b32_e64 v28, v28, v130, s[8:9]
	v_mul_f32_e32 v74, 0x37800000, v28
	v_cndmask_b32_e32 v28, v28, v74, vcc
	v_cmp_class_f32_e32 vcc, v70, v223
	v_mov_b32_e32 v191, v163
	v_mov_b32_e32 v163, v90
	v_cndmask_b32_e32 v28, v28, v70, vcc
	v_max_f32_e32 v70, 0x2b8cbccc, v28
	v_div_scale_f32 v74, s[8:9], v70, v70, 1.0
	v_rcp_f32_e32 v130, v74
	v_rcp_f32_e32 v28, v24
	v_add_f32_e32 v24, v25, v71
	v_mul_f32_e32 v150, 0xbfb8aa3b, v24
	v_fma_f32 v24, -v74, v130, 1.0
	v_fmac_f32_e32 v130, v24, v130
	v_div_scale_f32 v24, vcc, 1.0, v70, 1.0
	v_mul_f32_e32 v25, v24, v130
	v_fma_f32 v71, -v74, v25, v24
	v_fmac_f32_e32 v25, v71, v130
	v_fma_f32 v24, -v74, v25, v24
	v_div_fmas_f32 v24, v24, v130, v25
	v_div_fixup_f32 v130, v24, v70, 1.0
	v_pk_mul_f32 v[24:25], v[228:229], v[130:131] op_sel_hi:[1,0]
	v_pk_mul_f32 v[70:71], v[188:189], v[130:131] op_sel_hi:[1,0]
	v_pk_mul_f32 v[188:189], v[202:203], v[130:131] op_sel_hi:[1,0]
	v_pk_mul_f32 v[202:203], v[232:233], v[130:131] op_sel_hi:[1,0]
	v_pk_mul_f32 v[172:173], v[170:171], v[24:25]
	v_pk_mul_f32 v[176:177], v[176:177], v[70:71]
	v_pk_mul_f32 v[182:183], v[188:189], v[182:183]
	v_pk_mul_f32 v[196:197], v[202:203], v[196:197]
	v_cvt_pk_f16_f32 v231, v202, v203
	v_cvt_pk_f16_f32 v230, v188, v189
	v_cvt_pk_f16_f32 v229, v70, v71
	v_cvt_pk_f16_f32 v228, v24, v25
	v_cvt_pk_f16_f32 v168, v172, v173
	v_cvt_pk_f16_f32 v169, v176, v177
	v_cvt_pk_f16_f32 v170, v182, v183
	v_cvt_pk_f16_f32 v171, v196, v197
	global_store_dwordx4 v[0:1], v[228:231], off offset:-384
	global_store_dwordx4 v[0:1], v[168:171], off
	s_nop 1
	s_waitcnt vmcnt(9)
; #define LAS __attribute__((address_space(3)))
; __device__ __forceinline__ float fast_sigmoid(float x) { return __builtin_amdgcn_rcpf(1.f + __expf(-x)); }
; __device__ __forceinline__ void prep_rwkv_phase(const Params& p, LAS unsigned char* lds, int gw, int ngw, int wave, int lane) {
;     ...
;         for (int hf = 0; hf < 2; ++hf) {
;             h16x8 owr, odec, ok2, ov, okk, ob;
;             const int o_ = h * 64 + fq * 16 + hf * 8;
;             const u32x4 rc = *(const u32x4*)(prow + o_), kc = kcs[hf], vc = *(const u32x4*)(prow + 1024 + o_);
;             u32x4 rp = *(const u32x4*)(pprev + o_), vp = *(const u32x4*)(pprev + 1024 + o_); const u32x4 kp = kps[hf];
;             if (first) { rp = (u32x4){0u, 0u, 0u, 0u}; vp = rp; }
; #pragma unroll
;             for (int i2 = 0; i2 < 2; ++i2) {
;                 const int i = 2 * hf + i2, c = h * 64 + i * 16 + 4 * fq;
;                 const f32x4 mur = *(const LAS f32x4*)(PRM + c), muk = *(const LAS f32x4*)(PRM + 512 + c), muv = *(const LAS f32x4*)(PRM + 1024 + c);
;                 const f32x4 w04 = *(const LAS f32x4*)(PRM + 1536 + c), a04 = *(const LAS f32x4*)(PRM + 2048 + c), kk4 = *(const LAS f32x4*)(PRM + 2560 + c), ka4 = *(const LAS f32x4*)(PRM + 3072 + c), rk4 = *(const LAS f32x4*)(PRM + 3584 + c);
; #pragma unroll
;                 for (int j = 0; j < 4; ++j) {
;                     const int e8 = i2 * 4 + j, e = hf * 8 + e8; const unsigned wsel = (e8 >> 1); const bool hiw = e8 & 1;
;     ...
;                     const float rcur = PREP_GET(rc), rprv = PREP_GET(rp), kcur = PREP_GET(kc), kprv = PREP_GET(kp), vcur = PREP_GET(vc), vprv = PREP_GET(vp);
;     ...
;                     const float r = rcur + (rprv - rcur) * mur[j], k = kcur + (kprv - kcur) * muk[j], v = vcur + (vprv - vcur) * muv[j];
;                     const float dec = __expf(-0.60653066f * fast_sigmoid(w04[j] + accD[i][j]));
;                     const float a = fast_sigmoid(a04[j] + accA[i][j]);
;                     const float kraw = k * kk4[j], k2 = k * (1.f + (a - 1.f) * ka4[j]);
;                     const float kkn = kraw * inv, bn = kkn * a; sbr += bn * r; skr += k2 * r; sbo += r * k2 * rk4[j];
;                     okk[e8] = (h16)kkn; ob[e8] = (h16)bn;
;                     owr[e8] = (h16)(dec * r); odec[e8] = (h16)dec; ok2[e8] = (h16)k2; ov[e8] = (h16)v;
;                 }
;             }
	v_mov_b64_e32 v[168:169], v[98:99]
	v_mov_b64_e32 v[170:171], v[100:101]
	s_nop 0
	s_nop 1
	s_waitcnt vmcnt(8)
	v_mov_b64_e32 v[228:229], v[102:103]
	v_mov_b64_e32 v[230:231], v[104:105]
	s_nop 1
	s_waitcnt vmcnt(7)
	v_mov_b64_e32 v[232:233], v[114:115]
	v_mov_b64_e32 v[234:235], v[116:117]
	s_nop 1
	s_waitcnt vmcnt(6)
	v_mov_b64_e32 v[70:71], v[106:107]
	v_mov_b64_e32 v[72:73], v[108:109]
	v_mov_b32_e32 v162, v172
	v_mul_f32_e32 v90, v86, v90
	v_mul_f32_e32 v25, 0x3fb8aa3b, v132
	v_fma_f32 v132, v32, v90, 0
	v_mov_b32_e32 v90, v173
	v_mul_f32_e32 v32, v87, v91
	v_pk_fma_f32 v[162:163], v[86:87], v[162:163], 0 op_sel_hi:[0,1,0]
	v_fmac_f32_e32 v132, v33, v32
	v_mov_b32_e32 v32, v176
	v_mov_b32_e32 v33, v88
	v_mul_f32_e32 v88, v82, v88
	v_pk_fma_f32 v[86:87], v[86:87], v[90:91], v[162:163] op_sel:[1,0,0]
	v_fmac_f32_e32 v132, v34, v88
	v_mov_b32_e32 v88, v177
	v_mul_f32_e32 v34, v83, v89
	v_pk_fma_f32 v[32:33], v[82:83], v[32:33], v[86:87] op_sel_hi:[0,1,1]
	v_exp_f32_e32 v24, v150
	v_fmac_f32_e32 v132, v35, v34
	v_mov_b32_e32 v34, v182
	v_mov_b32_e32 v35, v174
	v_mul_f32_e32 v150, v92, v174
	v_pk_fma_f32 v[32:33], v[82:83], v[88:89], v[32:33] op_sel:[1,0,0]
	v_fmac_f32_e32 v132, v46, v150
	v_mov_b32_e32 v174, v183
	v_mul_f32_e32 v46, v93, v175
	v_pk_fma_f32 v[32:33], v[92:93], v[34:35], v[32:33] op_sel_hi:[0,1,1]
	v_fmac_f32_e32 v132, v47, v46
	v_mov_b32_e32 v46, v196
	v_mov_b32_e32 v47, v180
	v_mul_f32_e32 v150, v84, v180
	v_pk_fma_f32 v[32:33], v[92:93], v[174:175], v[32:33] op_sel:[1,0,0]
	v_add_f32_e32 v29, v29, v75
	v_fmac_f32_e32 v132, v48, v150
	v_pk_fma_f32 v[32:33], v[84:85], v[46:47], v[32:33] op_sel_hi:[0,1,1]
	v_mov_b32_e32 v180, v197
	v_mul_f32_e32 v34, v85, v181
	v_mul_f32_e32 v29, 0xbfb8aa3b, v29
	v_fmac_f32_e32 v132, v49, v34
	v_pk_fma_f32 v[34:35], v[84:85], v[180:181], v[32:33] op_sel:[1,0,0]
	v_pk_mul_f32 v[32:33], v[178:179], v[130:131] op_sel_hi:[1,0]
	v_exp_f32_e32 v29, v29
	v_mov_b32_e32 v46, v32
	v_mov_b32_e32 v47, v192
	v_mov_b32_e32 v187, v193
	v_pk_mul_f32 v[82:83], v[46:47], v[186:187]
	v_add_f32_e32 v24, 1.0, v24
	v_exp_f32_e32 v74, v25
	v_add_f32_e32 v25, -1.0, v28
	v_rcp_f32_e32 v24, v24
	v_mov_b32_e32 v200, v33
	v_fma_f32 v155, v58, v25, 1.0
	v_add_f32_e32 v25, 1.0, v29
	v_pk_mul_f32 v[84:85], v[200:201], v[160:161]
	v_rcp_f32_e32 v58, v25
	v_mul_f32_e32 v24, 0xbf1b4598, v24
	v_mul_f32_e32 v24, 0x3fb8aa3b, v24
	v_exp_f32_e32 v75, v24
	v_add_f32_e32 v24, -1.0, v58
	v_fma_f32 v153, v59, v24, 1.0
	v_cvt_pk_f16_f32 v24, v78, v79
	v_cvt_pk_f16_f32 v32, v32, v33
	v_mul_f32_e32 v26, 0xbfb8aa3b, v26
	v_mul_f32_e32 v27, 0xbfb8aa3b, v27
	v_exp_f32_e32 v26, v26
	v_exp_f32_e32 v27, v27
	v_mov_b32_e32 v29, v164
	v_mov_b32_e32 v59, v165
	v_add_f32_e32 v26, 1.0, v26
	v_add_f32_e32 v25, 1.0, v27
	v_rcp_f32_e32 v26, v26
	v_rcp_f32_e32 v25, v25
	v_pk_fma_f32 v[22:23], v[22:23], v[44:45], s[0:1]
	v_pk_mov_b32 v[20:21], v[20:21], v[30:31] op_sel:[1,0]
	v_mul_f32_e32 v26, 0xbf1b4598, v26
	v_mul_f32_e32 v25, 0xbf1b4598, v25
	v_mov_b32_e32 v22, v151
	s_nop 0
	v_cndmask_b32_e64 v49, v168, 0, s[6:7]
	v_lshlrev_b32_e32 v48, 16, v49
	s_nop 0
	v_lshlrev_b32_e32 v46, 16, v232
	v_and_b32_e32 v47, 0xffff0000, v232
	v_and_b32_e32 v49, 0xffff0000, v49
	v_pk_add_f32 v[48:49], v[48:49], v[46:47] neg_lo:[0,1] neg_hi:[0,1]
	v_cndmask_b32_e64 v89, v228, 0, s[6:7]
	v_pk_fma_f32 v[48:49], v[62:63], v[48:49], v[46:47]
	v_cndmask_b32_e64 v92, v169, 0, s[6:7]
	v_pk_mul_f32 v[46:47], v[48:49], v[82:83] op_sel_hi:[0,1]
	v_pk_fma_f32 v[34:35], v[48:49], v[82:83], v[34:35] op_sel_hi:[0,1,1]
	v_fmac_f32_e32 v132, v66, v47
	v_pk_mul_f32 v[62:63], v[48:49], v[84:85]
	v_pk_mul_f32 v[46:47], v[48:49], v[78:79]
	v_pk_fma_f32 v[34:35], v[48:49], v[84:85], v[34:35] op_sel:[1,0,0]
	v_fmac_f32_e32 v132, v67, v63
	s_nop 0
	v_lshlrev_b32_e32 v48, 16, v70
	v_and_b32_e32 v49, 0xffff0000, v70
	v_lshlrev_b32_e32 v62, 16, v89
	v_and_b32_e32 v63, 0xffff0000, v89
	v_pk_add_f32 v[62:63], v[62:63], v[48:49] neg_lo:[0,1] neg_hi:[0,1]
	v_lshlrev_b32_e32 v78, 16, v92
	v_pk_fma_f32 v[48:49], v[50:51], v[62:63], v[48:49]
	v_and_b32_e32 v79, 0xffff0000, v92
	v_cvt_pk_f16_f32 v50, v48, v49
	v_pk_mul_f32 v[48:49], v[158:159], v[130:131] op_sel_hi:[1,0]
	v_cndmask_b32_e64 v88, v229, 0, s[6:7]
	v_mov_b32_e32 v194, v48
	v_cvt_pk_f16_f32 v33, v48, v49
	v_mov_b32_e32 v166, v49
	v_lshlrev_b32_e32 v48, 16, v233
	v_and_b32_e32 v49, 0xffff0000, v233
	v_pk_add_f32 v[78:79], v[78:79], v[48:49] neg_lo:[0,1] neg_hi:[0,1]
	v_pk_mul_f32 v[62:63], v[194:195], v[184:185]
	v_pk_fma_f32 v[48:49], v[64:65], v[78:79], v[48:49]
	v_pk_mul_f32 v[66:67], v[166:167], v[190:191]
	v_pk_mul_f32 v[64:65], v[48:49], v[62:63] op_sel_hi:[0,1]
	v_fmac_f32_e32 v132, v68, v65
	v_pk_mul_f32 v[64:65], v[48:49], v[80:81]
	v_cvt_pk_f16_f32 v46, v46, v47
	v_pk_fma_f32 v[34:35], v[48:49], v[62:63], v[34:35] op_sel_hi:[0,1,1]
	v_cvt_pk_f16_f32 v47, v64, v65
	v_pk_mul_f32 v[64:65], v[48:49], v[66:67]
	v_pk_fma_f32 v[48:49], v[48:49], v[66:67], v[34:35] op_sel:[1,0,0]
	v_fmac_f32_e32 v132, v69, v65
	v_lshlrev_b32_e32 v34, 16, v71
	v_and_b32_e32 v35, 0xffff0000, v71
	v_lshlrev_b32_e32 v64, 16, v88
	v_and_b32_e32 v65, 0xffff0000, v88
	v_pk_add_f32 v[64:65], v[64:65], v[34:35] neg_lo:[0,1] neg_hi:[0,1]
	v_cndmask_b32_e64 v91, v170, 0, s[6:7]
	v_pk_fma_f32 v[34:35], v[52:53], v[64:65], v[34:35]
	v_lshlrev_b32_e32 v52, 16, v234
	v_cvt_pk_f16_f32 v51, v34, v35
	v_pk_mul_f32 v[34:35], v[156:157], v[130:131] op_sel_hi:[1,0]
	v_and_b32_e32 v53, 0xffff0000, v234
	v_lshlrev_b32_e32 v64, 16, v91
	v_and_b32_e32 v65, 0xffff0000, v91
	v_mov_b32_e32 v154, v34
	v_pk_add_f32 v[64:65], v[64:65], v[52:53] neg_lo:[0,1] neg_hi:[0,1]
	v_pk_mul_f32 v[28:29], v[154:155], v[28:29]
	v_mov_b32_e32 v152, v35
	s_waitcnt lgkmcnt(1)
; #define LAS __attribute__((address_space(3)))
; __device__ __forceinline__ float fast_sigmoid(float x) { return __builtin_amdgcn_rcpf(1.f + __expf(-x)); }
; __device__ __forceinline__ void prep_rwkv_phase(const Params& p, LAS unsigned char* lds, int gw, int ngw, int wave, int lane) {
;     ...
;         for (int hf = 0; hf < 2; ++hf) {
;             h16x8 owr, odec, ok2, ov, okk, ob;
;             const int o_ = h * 64 + fq * 16 + hf * 8;
;             const u32x4 rc = *(const u32x4*)(prow + o_), kc = kcs[hf], vc = *(const u32x4*)(prow + 1024 + o_);
;             u32x4 rp = *(const u32x4*)(pprev + o_), vp = *(const u32x4*)(pprev + 1024 + o_); const u32x4 kp = kps[hf];
;             if (first) { rp = (u32x4){0u, 0u, 0u, 0u}; vp = rp; }
; #pragma unroll
;             for (int i2 = 0; i2 < 2; ++i2) {
;                 const int i = 2 * hf + i2, c = h * 64 + i * 16 + 4 * fq;
;                 const f32x4 mur = *(const LAS f32x4*)(PRM + c), muk = *(const LAS f32x4*)(PRM + 512 + c), muv = *(const LAS f32x4*)(PRM + 1024 + c);
;                 const f32x4 w04 = *(const LAS f32x4*)(PRM + 1536 + c), a04 = *(const LAS f32x4*)(PRM + 2048 + c), kk4 = *(const LAS f32x4*)(PRM + 2560 + c), ka4 = *(const LAS f32x4*)(PRM + 3072 + c), rk4 = *(const LAS f32x4*)(PRM + 3584 + c);
; #pragma unroll
;                 for (int j = 0; j < 4; ++j) {
;                     const int e8 = i2 * 4 + j, e = hf * 8 + e8; const unsigned wsel = (e8 >> 1); const bool hiw = e8 & 1;
;     ...
;                     const float rcur = PREP_GET(rc), rprv = PREP_GET(rp), kcur = PREP_GET(kc), kprv = PREP_GET(kp), vcur = PREP_GET(vc), vprv = PREP_GET(vp);
;     ...
;                     const float r = rcur + (rprv - rcur) * mur[j], k = kcur + (kprv - kcur) * muk[j], v = vcur + (vprv - vcur) * muv[j];
;                     const float dec = __expf(-0.60653066f * fast_sigmoid(w04[j] + accD[i][j]));
;                     const float a = fast_sigmoid(a04[j] + accA[i][j]);
;                     const float kraw = k * kk4[j], k2 = k * (1.f + (a - 1.f) * ka4[j]);
;                     const float kkn = kraw * inv, bn = kkn * a; sbr += bn * r; skr += k2 * r; sbo += r * k2 * rk4[j];
;                     okk[e8] = (h16)kkn; ob[e8] = (h16)bn;
;                     owr[e8] = (h16)(dec * r); odec[e8] = (h16)dec; ok2[e8] = (h16)k2; ov[e8] = (h16)v;
;                 }
;             }
	v_pk_fma_f32 v[40:41], v[64:65], v[40:41], v[52:53]
	v_pk_mul_f32 v[58:59], v[152:153], v[58:59]
	v_pk_mul_f32 v[52:53], v[40:41], v[28:29] op_sel_hi:[0,1]
	v_cndmask_b32_e64 v87, v230, 0, s[6:7]
	v_fmac_f32_e32 v132, v54, v53
	v_pk_mul_f32 v[52:53], v[40:41], v[58:59]
	v_lshlrev_b32_e32 v54, 16, v87
	v_fmac_f32_e32 v132, v55, v53
	v_lshlrev_b32_e32 v52, 16, v72
	v_and_b32_e32 v53, 0xffff0000, v72
	v_and_b32_e32 v55, 0xffff0000, v87
	v_pk_add_f32 v[54:55], v[54:55], v[52:53] neg_lo:[0,1] neg_hi:[0,1]
	v_mul_f32_e32 v26, 0x3fb8aa3b, v26
	s_waitcnt lgkmcnt(0)
	v_pk_fma_f32 v[36:37], v[54:55], v[36:37], v[52:53]
	v_mul_f32_e32 v25, 0x3fb8aa3b, v25
	v_cvt_pk_f16_f32 v52, v36, v37
	v_pk_mul_f32 v[36:37], v[60:61], v[130:131]
	v_cndmask_b32_e64 v90, v171, 0, s[6:7]
	v_mov_b32_e32 v37, v23
	v_mov_b32_e32 v23, v44
	v_pk_mul_f32 v[44:45], v[36:37], v[22:23]
	v_pk_mul_f32 v[22:23], v[198:199], v[130:131]
	v_pk_fma_f32 v[54:55], v[76:77], v[30:31], s[0:1]
	v_exp_f32_e32 v188, v26
	v_exp_f32_e32 v189, v25
	v_cvt_pk_f16_f32 v34, v34, v35
	v_mov_b32_e32 v23, v55
	v_cvt_pk_f16_f32 v35, v36, v22
	v_lshlrev_b32_e32 v36, 16, v235
	v_and_b32_e32 v37, 0xffff0000, v235
	v_lshlrev_b32_e32 v54, 16, v90
	v_and_b32_e32 v55, 0xffff0000, v90
	v_pk_add_f32 v[54:55], v[54:55], v[36:37] neg_lo:[0,1] neg_hi:[0,1]
	v_pk_fma_f32 v[64:65], v[40:41], v[28:29], v[48:49] op_sel_hi:[0,1,1]
	v_pk_fma_f32 v[36:37], v[54:55], v[42:43], v[36:37]
	v_pk_mul_f32 v[48:49], v[40:41], v[74:75]
	v_pk_mul_f32 v[42:43], v[36:37], v[44:45] op_sel_hi:[0,1]
	v_pk_fma_f32 v[40:41], v[40:41], v[58:59], v[64:65] op_sel:[1,0,0]
	v_pk_mul_f32 v[30:31], v[22:23], v[20:21]
	v_fmac_f32_e32 v132, v56, v43
	v_pk_mul_f32 v[42:43], v[36:37], v[188:189]
	v_cndmask_b32_e64 v86, v231, 0, s[6:7]
	v_cvt_pk_f16_f32 v48, v48, v49
	v_pk_fma_f32 v[40:41], v[36:37], v[44:45], v[40:41] op_sel_hi:[0,1,1]
	v_cvt_pk_f16_f32 v49, v42, v43
	v_pk_mul_f32 v[42:43], v[36:37], v[30:31]
	v_cvt_pk_f16_f32 v23, v44, v30
	v_cvt_pk_f16_f32 v22, v28, v58
	v_pk_fma_f32 v[36:37], v[36:37], v[30:31], v[40:41] op_sel:[1,0,0]
	v_fmac_f32_e32 v132, v57, v43
	v_cvt_pk_f16_f32 v43, v45, v31
	v_cvt_pk_f16_f32 v42, v29, v59
	v_lshlrev_b32_e32 v28, 16, v73
	v_and_b32_e32 v29, 0xffff0000, v73
	v_lshlrev_b32_e32 v30, 16, v86
	v_and_b32_e32 v31, 0xffff0000, v86
	v_pk_add_f32 v[30:31], v[30:31], v[28:29] neg_lo:[0,1] neg_hi:[0,1]
	v_cvt_pk_f16_f32 v21, v62, v66
	v_pk_fma_f32 v[28:29], v[30:31], v[38:39], v[28:29]
	ds_bpermute_b32 v30, v145, v36
	ds_bpermute_b32 v31, v145, v37
	v_cvt_pk_f16_f32 v53, v28, v29
	ds_bpermute_b32 v28, v145, v132
	v_cvt_pk_f16_f32 v20, v82, v84
	global_store_dwordx4 v[0:1], v[20:23], off offset:16
	v_cvt_pk_f16_f32 v27, v188, v189
	v_cvt_pk_f16_f32 v26, v74, v75
	s_waitcnt lgkmcnt(1)
	v_pk_add_f32 v[20:21], v[36:37], v[30:31]
	s_waitcnt lgkmcnt(0)
	v_add_f32_e32 v28, v132, v28
	ds_bpermute_b32 v22, v2, v20
	ds_bpermute_b32 v23, v2, v21
	ds_bpermute_b32 v2, v2, v28
	v_cvt_pk_f16_f32 v25, v80, v81
	v_cvt_pk_f16_f32 v41, v63, v67
	v_cvt_pk_f16_f32 v40, v83, v85
	global_store_dwordx4 v[0:1], v[32:35], off offset:-368
	global_store_dwordx4 v[0:1], v[46:49], off offset:-240
	global_store_dwordx4 v[0:1], v[24:27], off offset:-112
	global_store_dwordx4 v[0:1], v[40:43], off offset:144
	global_store_dwordx4 v[0:1], v[50:53], off offset:272
	s_and_saveexec_b64 s[8:9], s[4:5]
	s_cbranch_execz .LBB0_860
	v_lshl_add_u64 v[24:25], s[92:93], 0, v[138:139]
	s_waitcnt lgkmcnt(1)
	v_pk_add_f32 v[0:1], v[20:21], v[22:23]
	s_waitcnt lgkmcnt(0)
	v_add_f32_e32 v2, v28, v2
	global_store_dwordx4 v[24:25], v[0:3], off
